# prologue/epilogue de-serialisation: P0 GEMV ada_b load (loop-invariant address) requested once before the reduction barrier instead of per batch row inside the loop; on top of v115
# baseline (speedup 1.0000x reference)
.LBB0_33:
	s_add_i32 s1, s71, 0x5f
	ds_write_b128 v35, v[2:5] offset:16384
	ds_write_b128 v35, v[6:9] offset:17408
	ds_write_b128 v35, v[10:13] offset:18432
	ds_write_b128 v35, v[14:17] offset:19456
	ds_write_b128 v35, v[18:21] offset:20480
	s_cmpk_lt_u32 s1, 0xbf
	s_mul_hi_i32 s1, s72, 0x78000
	s_mul_i32 s72, s72, 0x78000
	v_or_b32_sdwa v2, v0, s0 dst_sel:DWORD dst_unused:UNUSED_PAD src0_sel:BYTE_0 src1_sel:DWORD
	s_cselect_b64 s[2:3], -1, 0
	s_add_u32 s4, s7, s72
	v_ashrrev_i32_e32 v3, 31, v2
	s_addc_u32 s5, s12, s1
	v_lshlrev_b64 v[4:5], 2, v[2:3]
	v_lshl_add_u64 v[2:3], s[26:27], 0, v[4:5]
	global_load_dword v210, v[2:3], off
	v_lshl_add_u64 v[4:5], s[4:5], 0, v[4:5]
	s_mov_b64 s[0:1], 0
	v_mov_b32_e32 v6, v54
	v_mov_b32_e32 v7, v53
	v_mov_b32_e32 v8, v52
	s_waitcnt lgkmcnt(0)
	s_barrier
	s_waitcnt vmcnt(0)
	s_branch .LBB0_35

.LBB0_35:
	ds_read2st64_b32 v[10:11], v8 offset1:20
	ds_read2st64_b32 v[12:13], v8 offset0:40 offset1:60
	ds_read2st64_b32 v[14:15], v8 offset0:80 offset1:100
	ds_read2st64_b32 v[16:17], v8 offset0:120 offset1:140
	s_and_b64 vcc, exec, s[2:3]
	s_waitcnt lgkmcnt(3)
	v_add_f32_e32 v9, 0, v10
	v_add_f32_e32 v9, v9, v11
	s_waitcnt lgkmcnt(2)
	v_add_f32_e32 v9, v9, v12
	v_add_f32_e32 v9, v9, v13
	s_waitcnt lgkmcnt(1)
	v_add_f32_e32 v9, v9, v14
	v_add_f32_e32 v9, v9, v15
	s_waitcnt lgkmcnt(0)
	v_add_f32_e32 v9, v9, v16
	v_add_f32_e32 v9, v9, v17
	s_cbranch_vccz .LBB0_34
	v_add_f32_e32 v9, v9, v210
	s_branch .LBB0_34
